# grid barrier: XCD leader publishes the per-XCD generation before its own acquire invalidate (non-leaders released ~one buffer_inv earlier)
# baseline (speedup 1.0000x reference)
.LBB0_1421:
	s_or_b64 exec, exec, s[4:5]
	s_mov_b64 s[4:5], exec
	v_mbcnt_lo_u32_b32 v0, s4, 0
	v_mbcnt_hi_u32_b32 v0, s5, v0
	v_cmp_eq_u32_e32 vcc, 0, v0
	s_waitcnt vmcnt(0)
	s_and_saveexec_b64 s[8:9], vcc
	s_cbranch_execz .LBB0_1423
	s_bcnt1_i32_b64 s4, s[4:5]
	v_mov_b32_e32 v0, s4
	v_mov_b32_e32 v1, 0x2000
	global_atomic_add v1, v0, s[6:7] offset:1024
.LBB0_1423:
	s_or_b64 exec, exec, s[8:9]
	buffer_inv sc1
	s_waitcnt vmcnt(0)
